# all three RMSNorm latent loops hand-written (per-row rstd in lanes, wide LDS stores), no prefetch
# baseline (speedup 1.0000x reference)
.LBB0_1323:
	v_mbcnt_lo_u32_b32 v119, -1, 0
	v_mbcnt_hi_u32_b32 v119, -1, v119
	v_and_b32_e32 v119, 15, v119
	v_lshlrev_b32_e32 v117, 2, v119
	s_lshl_b32 s10, s3, 4
	v_mov_b32_e32 v116, s10
.Lnm_fin_loop:
	s_add_i32 s8, s4, -15
	s_ashr_i32 s9, s8, 31
	s_lshl_b64 s[10:11], s[8:9], 13
	s_mov_b64 s[24:25], s[10:11]
	v_lshl_add_u64 v[124:125], v[68:69], 0, s[10:11]
	global_load_dwordx4 v[4:7], v[124:125], off
	s_add_u32 s10, s10, 0x2000
	s_addc_u32 s11, s11, 0
	v_lshl_add_u64 v[124:125], v[68:69], 0, s[10:11]
	global_load_dwordx4 v[8:11], v[124:125], off
	s_add_u32 s10, s10, 0x2000
	s_addc_u32 s11, s11, 0
	v_lshl_add_u64 v[124:125], v[68:69], 0, s[10:11]
	global_load_dwordx4 v[12:15], v[124:125], off
	s_add_u32 s10, s10, 0x2000
	s_addc_u32 s11, s11, 0
	v_lshl_add_u64 v[124:125], v[68:69], 0, s[10:11]
	global_load_dwordx4 v[16:19], v[124:125], off
	s_add_u32 s10, s10, 0x2000
	s_addc_u32 s11, s11, 0
	v_lshl_add_u64 v[124:125], v[68:69], 0, s[10:11]
	global_load_dwordx4 v[20:23], v[124:125], off
	s_add_u32 s10, s10, 0x2000
	s_addc_u32 s11, s11, 0
	v_lshl_add_u64 v[124:125], v[68:69], 0, s[10:11]
	global_load_dwordx4 v[24:27], v[124:125], off
	s_add_u32 s10, s10, 0x2000
	s_addc_u32 s11, s11, 0
	v_lshl_add_u64 v[124:125], v[68:69], 0, s[10:11]
	global_load_dwordx4 v[28:31], v[124:125], off
	s_add_u32 s10, s10, 0x2000
	s_addc_u32 s11, s11, 0
	v_lshl_add_u64 v[124:125], v[68:69], 0, s[10:11]
	global_load_dwordx4 v[32:35], v[124:125], off
	s_add_u32 s10, s10, 0x2000
	s_addc_u32 s11, s11, 0
	v_lshl_add_u64 v[124:125], v[68:69], 0, s[10:11]
	global_load_dwordx4 v[36:39], v[124:125], off
	s_add_u32 s10, s10, 0x2000
	s_addc_u32 s11, s11, 0
	v_lshl_add_u64 v[124:125], v[68:69], 0, s[10:11]
	global_load_dwordx4 v[40:43], v[124:125], off
	s_add_u32 s10, s10, 0x2000
	s_addc_u32 s11, s11, 0
	v_lshl_add_u64 v[124:125], v[68:69], 0, s[10:11]
	global_load_dwordx4 v[44:47], v[124:125], off
	s_add_u32 s10, s10, 0x2000
	s_addc_u32 s11, s11, 0
	v_lshl_add_u64 v[124:125], v[68:69], 0, s[10:11]
	global_load_dwordx4 v[48:51], v[124:125], off
	s_add_u32 s10, s10, 0x2000
	s_addc_u32 s11, s11, 0
	v_lshl_add_u64 v[124:125], v[68:69], 0, s[10:11]
	global_load_dwordx4 v[52:55], v[124:125], off
	s_add_u32 s10, s10, 0x2000
	s_addc_u32 s11, s11, 0
	v_lshl_add_u64 v[124:125], v[68:69], 0, s[10:11]
	global_load_dwordx4 v[56:59], v[124:125], off
	s_add_u32 s10, s10, 0x2000
	s_addc_u32 s11, s11, 0
	v_lshl_add_u64 v[124:125], v[68:69], 0, s[10:11]
	global_load_dwordx4 v[60:63], v[124:125], off
	s_add_u32 s10, s10, 0x2000
	s_addc_u32 s11, s11, 0
	v_lshl_add_u64 v[124:125], v[68:69], 0, s[10:11]
	global_load_dwordx4 v[64:67], v[124:125], off
	s_waitcnt vmcnt(15)
	v_mul_f32_e32 v84, v5, v5
	v_mul_f32_e32 v100, v7, v7
	v_fmac_f32_e32 v84, v4, v4
	v_fmac_f32_e32 v100, v6, v6
	v_add_f32_e32 v84, v84, v100
	s_waitcnt vmcnt(14)
	v_mul_f32_e32 v85, v9, v9
	v_mul_f32_e32 v101, v11, v11
	v_fmac_f32_e32 v85, v8, v8
	v_fmac_f32_e32 v101, v10, v10
	v_add_f32_e32 v85, v85, v101
	s_waitcnt vmcnt(13)
	v_mul_f32_e32 v86, v13, v13
	v_mul_f32_e32 v102, v15, v15
	v_fmac_f32_e32 v86, v12, v12
	v_fmac_f32_e32 v102, v14, v14
	v_add_f32_e32 v86, v86, v102
	s_waitcnt vmcnt(12)
	v_mul_f32_e32 v87, v17, v17
	v_mul_f32_e32 v103, v19, v19
	v_fmac_f32_e32 v87, v16, v16
	v_fmac_f32_e32 v103, v18, v18
	v_add_f32_e32 v87, v87, v103
	s_waitcnt vmcnt(11)
	v_mul_f32_e32 v88, v21, v21
	v_mul_f32_e32 v104, v23, v23
	v_fmac_f32_e32 v88, v20, v20
	v_fmac_f32_e32 v104, v22, v22
	v_add_f32_e32 v88, v88, v104
	s_waitcnt vmcnt(10)
	v_mul_f32_e32 v89, v25, v25
	v_mul_f32_e32 v105, v27, v27
	v_fmac_f32_e32 v89, v24, v24
	v_fmac_f32_e32 v105, v26, v26
	v_add_f32_e32 v89, v89, v105
	s_waitcnt vmcnt(9)
	v_mul_f32_e32 v90, v29, v29
	v_mul_f32_e32 v106, v31, v31
	v_fmac_f32_e32 v90, v28, v28
	v_fmac_f32_e32 v106, v30, v30
	v_add_f32_e32 v90, v90, v106
	s_waitcnt vmcnt(8)
	v_mul_f32_e32 v91, v33, v33
	v_mul_f32_e32 v107, v35, v35
	v_fmac_f32_e32 v91, v32, v32
	v_fmac_f32_e32 v107, v34, v34
	v_add_f32_e32 v91, v91, v107
	s_waitcnt vmcnt(7)
	v_mul_f32_e32 v92, v37, v37
	v_mul_f32_e32 v108, v39, v39
	v_fmac_f32_e32 v92, v36, v36
	v_fmac_f32_e32 v108, v38, v38
	v_add_f32_e32 v92, v92, v108
	s_waitcnt vmcnt(6)
	v_mul_f32_e32 v93, v41, v41
	v_mul_f32_e32 v109, v43, v43
	v_fmac_f32_e32 v93, v40, v40
	v_fmac_f32_e32 v109, v42, v42
	v_add_f32_e32 v93, v93, v109
	s_waitcnt vmcnt(5)
	v_mul_f32_e32 v94, v45, v45
	v_mul_f32_e32 v110, v47, v47
	v_fmac_f32_e32 v94, v44, v44
	v_fmac_f32_e32 v110, v46, v46
	v_add_f32_e32 v94, v94, v110
	s_waitcnt vmcnt(4)
	v_mul_f32_e32 v95, v49, v49
	v_mul_f32_e32 v111, v51, v51
	v_fmac_f32_e32 v95, v48, v48
	v_fmac_f32_e32 v111, v50, v50
	v_add_f32_e32 v95, v95, v111
	s_waitcnt vmcnt(3)
	v_mul_f32_e32 v96, v53, v53
	v_mul_f32_e32 v112, v55, v55
	v_fmac_f32_e32 v96, v52, v52
	v_fmac_f32_e32 v112, v54, v54
	v_add_f32_e32 v96, v96, v112
	s_waitcnt vmcnt(2)
	v_mul_f32_e32 v97, v57, v57
	v_mul_f32_e32 v113, v59, v59
	v_fmac_f32_e32 v97, v56, v56
	v_fmac_f32_e32 v113, v58, v58
	v_add_f32_e32 v97, v97, v113
	s_waitcnt vmcnt(1)
	v_mul_f32_e32 v98, v61, v61
	v_mul_f32_e32 v114, v63, v63
	v_fmac_f32_e32 v98, v60, v60
	v_fmac_f32_e32 v114, v62, v62
	v_add_f32_e32 v98, v98, v114
	s_waitcnt vmcnt(0)
	v_mul_f32_e32 v99, v65, v65
	v_mul_f32_e32 v115, v67, v67
	v_fmac_f32_e32 v99, v64, v64
	v_fmac_f32_e32 v115, v66, v66
	v_add_f32_e32 v99, v99, v115
	ds_bpermute_b32 v100, v73, v84
	ds_bpermute_b32 v101, v73, v85
	ds_bpermute_b32 v102, v73, v86
	ds_bpermute_b32 v103, v73, v87
	ds_bpermute_b32 v104, v73, v88
	ds_bpermute_b32 v105, v73, v89
	ds_bpermute_b32 v106, v73, v90
	ds_bpermute_b32 v107, v73, v91
	ds_bpermute_b32 v108, v73, v92
	ds_bpermute_b32 v109, v73, v93
	ds_bpermute_b32 v110, v73, v94
	ds_bpermute_b32 v111, v73, v95
	ds_bpermute_b32 v112, v73, v96
	ds_bpermute_b32 v113, v73, v97
	ds_bpermute_b32 v114, v73, v98
	ds_bpermute_b32 v115, v73, v99
	s_waitcnt lgkmcnt(15)
	v_add_f32_e32 v84, v84, v100
	s_waitcnt lgkmcnt(14)
	v_add_f32_e32 v85, v85, v101
	s_waitcnt lgkmcnt(13)
	v_add_f32_e32 v86, v86, v102
	s_waitcnt lgkmcnt(12)
	v_add_f32_e32 v87, v87, v103
	s_waitcnt lgkmcnt(11)
	v_add_f32_e32 v88, v88, v104
	s_waitcnt lgkmcnt(10)
	v_add_f32_e32 v89, v89, v105
	s_waitcnt lgkmcnt(9)
	v_add_f32_e32 v90, v90, v106
	s_waitcnt lgkmcnt(8)
	v_add_f32_e32 v91, v91, v107
	s_waitcnt lgkmcnt(7)
	v_add_f32_e32 v92, v92, v108
	s_waitcnt lgkmcnt(6)
	v_add_f32_e32 v93, v93, v109
	s_waitcnt lgkmcnt(5)
	v_add_f32_e32 v94, v94, v110
	s_waitcnt lgkmcnt(4)
	v_add_f32_e32 v95, v95, v111
	s_waitcnt lgkmcnt(3)
	v_add_f32_e32 v96, v96, v112
	s_waitcnt lgkmcnt(2)
	v_add_f32_e32 v97, v97, v113
	s_waitcnt lgkmcnt(1)
	v_add_f32_e32 v98, v98, v114
	s_waitcnt lgkmcnt(0)
	v_add_f32_e32 v99, v99, v115
	ds_bpermute_b32 v100, v74, v84
	ds_bpermute_b32 v101, v74, v85
	ds_bpermute_b32 v102, v74, v86
	ds_bpermute_b32 v103, v74, v87
	ds_bpermute_b32 v104, v74, v88
	ds_bpermute_b32 v105, v74, v89
	ds_bpermute_b32 v106, v74, v90
	ds_bpermute_b32 v107, v74, v91
	ds_bpermute_b32 v108, v74, v92
	ds_bpermute_b32 v109, v74, v93
	ds_bpermute_b32 v110, v74, v94
	ds_bpermute_b32 v111, v74, v95
	ds_bpermute_b32 v112, v74, v96
	ds_bpermute_b32 v113, v74, v97
	ds_bpermute_b32 v114, v74, v98
	ds_bpermute_b32 v115, v74, v99
	s_waitcnt lgkmcnt(15)
	v_add_f32_e32 v84, v84, v100
	s_waitcnt lgkmcnt(14)
	v_add_f32_e32 v85, v85, v101
	s_waitcnt lgkmcnt(13)
	v_add_f32_e32 v86, v86, v102
	s_waitcnt lgkmcnt(12)
	v_add_f32_e32 v87, v87, v103
	s_waitcnt lgkmcnt(11)
	v_add_f32_e32 v88, v88, v104
	s_waitcnt lgkmcnt(10)
	v_add_f32_e32 v89, v89, v105
	s_waitcnt lgkmcnt(9)
	v_add_f32_e32 v90, v90, v106
	s_waitcnt lgkmcnt(8)
	v_add_f32_e32 v91, v91, v107
	s_waitcnt lgkmcnt(7)
	v_add_f32_e32 v92, v92, v108
	s_waitcnt lgkmcnt(6)
	v_add_f32_e32 v93, v93, v109
	s_waitcnt lgkmcnt(5)
	v_add_f32_e32 v94, v94, v110
	s_waitcnt lgkmcnt(4)
	v_add_f32_e32 v95, v95, v111
	s_waitcnt lgkmcnt(3)
	v_add_f32_e32 v96, v96, v112
	s_waitcnt lgkmcnt(2)
	v_add_f32_e32 v97, v97, v113
	s_waitcnt lgkmcnt(1)
	v_add_f32_e32 v98, v98, v114
	s_waitcnt lgkmcnt(0)
	v_add_f32_e32 v99, v99, v115
	ds_bpermute_b32 v100, v75, v84
	ds_bpermute_b32 v101, v75, v85
	ds_bpermute_b32 v102, v75, v86
	ds_bpermute_b32 v103, v75, v87
	ds_bpermute_b32 v104, v75, v88
	ds_bpermute_b32 v105, v75, v89
	ds_bpermute_b32 v106, v75, v90
	ds_bpermute_b32 v107, v75, v91
	ds_bpermute_b32 v108, v75, v92
	ds_bpermute_b32 v109, v75, v93
	ds_bpermute_b32 v110, v75, v94
	ds_bpermute_b32 v111, v75, v95
	ds_bpermute_b32 v112, v75, v96
	ds_bpermute_b32 v113, v75, v97
	ds_bpermute_b32 v114, v75, v98
	ds_bpermute_b32 v115, v75, v99
	s_waitcnt lgkmcnt(15)
	v_add_f32_e32 v84, v84, v100
	s_waitcnt lgkmcnt(14)
	v_add_f32_e32 v85, v85, v101
	s_waitcnt lgkmcnt(13)
	v_add_f32_e32 v86, v86, v102
	s_waitcnt lgkmcnt(12)
	v_add_f32_e32 v87, v87, v103
	s_waitcnt lgkmcnt(11)
	v_add_f32_e32 v88, v88, v104
	s_waitcnt lgkmcnt(10)
	v_add_f32_e32 v89, v89, v105
	s_waitcnt lgkmcnt(9)
	v_add_f32_e32 v90, v90, v106
	s_waitcnt lgkmcnt(8)
	v_add_f32_e32 v91, v91, v107
	s_waitcnt lgkmcnt(7)
	v_add_f32_e32 v92, v92, v108
	s_waitcnt lgkmcnt(6)
	v_add_f32_e32 v93, v93, v109
	s_waitcnt lgkmcnt(5)
	v_add_f32_e32 v94, v94, v110
	s_waitcnt lgkmcnt(4)
	v_add_f32_e32 v95, v95, v111
	s_waitcnt lgkmcnt(3)
	v_add_f32_e32 v96, v96, v112
	s_waitcnt lgkmcnt(2)
	v_add_f32_e32 v97, v97, v113
	s_waitcnt lgkmcnt(1)
	v_add_f32_e32 v98, v98, v114
	s_waitcnt lgkmcnt(0)
	v_add_f32_e32 v99, v99, v115
	ds_bpermute_b32 v100, v76, v84
	ds_bpermute_b32 v101, v76, v85
	ds_bpermute_b32 v102, v76, v86
	ds_bpermute_b32 v103, v76, v87
	ds_bpermute_b32 v104, v76, v88
	ds_bpermute_b32 v105, v76, v89
	ds_bpermute_b32 v106, v76, v90
	ds_bpermute_b32 v107, v76, v91
	ds_bpermute_b32 v108, v76, v92
	ds_bpermute_b32 v109, v76, v93
	ds_bpermute_b32 v110, v76, v94
	ds_bpermute_b32 v111, v76, v95
	ds_bpermute_b32 v112, v76, v96
	ds_bpermute_b32 v113, v76, v97
	ds_bpermute_b32 v114, v76, v98
	ds_bpermute_b32 v115, v76, v99
	s_waitcnt lgkmcnt(15)
	v_add_f32_e32 v84, v84, v100
	s_waitcnt lgkmcnt(14)
	v_add_f32_e32 v85, v85, v101
	s_waitcnt lgkmcnt(13)
	v_add_f32_e32 v86, v86, v102
	s_waitcnt lgkmcnt(12)
	v_add_f32_e32 v87, v87, v103
	s_waitcnt lgkmcnt(11)
	v_add_f32_e32 v88, v88, v104
	s_waitcnt lgkmcnt(10)
	v_add_f32_e32 v89, v89, v105
	s_waitcnt lgkmcnt(9)
	v_add_f32_e32 v90, v90, v106
	s_waitcnt lgkmcnt(8)
	v_add_f32_e32 v91, v91, v107
	s_waitcnt lgkmcnt(7)
	v_add_f32_e32 v92, v92, v108
	s_waitcnt lgkmcnt(6)
	v_add_f32_e32 v93, v93, v109
	s_waitcnt lgkmcnt(5)
	v_add_f32_e32 v94, v94, v110
	s_waitcnt lgkmcnt(4)
	v_add_f32_e32 v95, v95, v111
	s_waitcnt lgkmcnt(3)
	v_add_f32_e32 v96, v96, v112
	s_waitcnt lgkmcnt(2)
	v_add_f32_e32 v97, v97, v113
	s_waitcnt lgkmcnt(1)
	v_add_f32_e32 v98, v98, v114
	s_waitcnt lgkmcnt(0)
	v_add_f32_e32 v99, v99, v115
	ds_bpermute_b32 v100, v77, v84
	ds_bpermute_b32 v101, v77, v85
	ds_bpermute_b32 v102, v77, v86
	ds_bpermute_b32 v103, v77, v87
	ds_bpermute_b32 v104, v77, v88
	ds_bpermute_b32 v105, v77, v89
	ds_bpermute_b32 v106, v77, v90
	ds_bpermute_b32 v107, v77, v91
	ds_bpermute_b32 v108, v77, v92
	ds_bpermute_b32 v109, v77, v93
	ds_bpermute_b32 v110, v77, v94
	ds_bpermute_b32 v111, v77, v95
	ds_bpermute_b32 v112, v77, v96
	ds_bpermute_b32 v113, v77, v97
	ds_bpermute_b32 v114, v77, v98
	ds_bpermute_b32 v115, v77, v99
	s_waitcnt lgkmcnt(15)
	v_add_f32_e32 v84, v84, v100
	s_waitcnt lgkmcnt(14)
	v_add_f32_e32 v85, v85, v101
	s_waitcnt lgkmcnt(13)
	v_add_f32_e32 v86, v86, v102
	s_waitcnt lgkmcnt(12)
	v_add_f32_e32 v87, v87, v103
	s_waitcnt lgkmcnt(11)
	v_add_f32_e32 v88, v88, v104
	s_waitcnt lgkmcnt(10)
	v_add_f32_e32 v89, v89, v105
	s_waitcnt lgkmcnt(9)
	v_add_f32_e32 v90, v90, v106
	s_waitcnt lgkmcnt(8)
	v_add_f32_e32 v91, v91, v107
	s_waitcnt lgkmcnt(7)
	v_add_f32_e32 v92, v92, v108
	s_waitcnt lgkmcnt(6)
	v_add_f32_e32 v93, v93, v109
	s_waitcnt lgkmcnt(5)
	v_add_f32_e32 v94, v94, v110
	s_waitcnt lgkmcnt(4)
	v_add_f32_e32 v95, v95, v111
	s_waitcnt lgkmcnt(3)
	v_add_f32_e32 v96, v96, v112
	s_waitcnt lgkmcnt(2)
	v_add_f32_e32 v97, v97, v113
	s_waitcnt lgkmcnt(1)
	v_add_f32_e32 v98, v98, v114
	s_waitcnt lgkmcnt(0)
	v_add_f32_e32 v99, v99, v115
	ds_bpermute_b32 v100, v78, v84
	ds_bpermute_b32 v101, v78, v85
	ds_bpermute_b32 v102, v78, v86
	ds_bpermute_b32 v103, v78, v87
	ds_bpermute_b32 v104, v78, v88
	ds_bpermute_b32 v105, v78, v89
	ds_bpermute_b32 v106, v78, v90
	ds_bpermute_b32 v107, v78, v91
	ds_bpermute_b32 v108, v78, v92
	ds_bpermute_b32 v109, v78, v93
	ds_bpermute_b32 v110, v78, v94
	ds_bpermute_b32 v111, v78, v95
	ds_bpermute_b32 v112, v78, v96
	ds_bpermute_b32 v113, v78, v97
	ds_bpermute_b32 v114, v78, v98
	ds_bpermute_b32 v115, v78, v99
	s_waitcnt lgkmcnt(15)
	v_add_f32_e32 v84, v84, v100
	s_waitcnt lgkmcnt(14)
	v_add_f32_e32 v85, v85, v101
	s_waitcnt lgkmcnt(13)
	v_add_f32_e32 v86, v86, v102
	s_waitcnt lgkmcnt(12)
	v_add_f32_e32 v87, v87, v103
	s_waitcnt lgkmcnt(11)
	v_add_f32_e32 v88, v88, v104
	s_waitcnt lgkmcnt(10)
	v_add_f32_e32 v89, v89, v105
	s_waitcnt lgkmcnt(9)
	v_add_f32_e32 v90, v90, v106
	s_waitcnt lgkmcnt(8)
	v_add_f32_e32 v91, v91, v107
	s_waitcnt lgkmcnt(7)
	v_add_f32_e32 v92, v92, v108
	s_waitcnt lgkmcnt(6)
	v_add_f32_e32 v93, v93, v109
	s_waitcnt lgkmcnt(5)
	v_add_f32_e32 v94, v94, v110
	s_waitcnt lgkmcnt(4)
	v_add_f32_e32 v95, v95, v111
	s_waitcnt lgkmcnt(3)
	v_add_f32_e32 v96, v96, v112
	s_waitcnt lgkmcnt(2)
	v_add_f32_e32 v97, v97, v113
	s_waitcnt lgkmcnt(1)
	v_add_f32_e32 v98, v98, v114
	s_waitcnt lgkmcnt(0)
	v_add_f32_e32 v99, v99, v115
	s_mov_b64 exec, 1
	ds_write_b128 v116, v[84:87]
	ds_write_b128 v116, v[88:91] offset:16
	ds_write_b128 v116, v[92:95] offset:32
	ds_write_b128 v116, v[96:99] offset:48
	s_mov_b64 exec, -1
	s_waitcnt lgkmcnt(0)
	s_barrier
	ds_read_b32 v128, v117
	ds_read_b32 v129, v117 offset:64
	ds_read_b32 v130, v117 offset:128
	ds_read_b32 v131, v117 offset:192
	ds_read_b32 v132, v117 offset:256
	ds_read_b32 v133, v117 offset:320
	ds_read_b32 v134, v117 offset:384
	ds_read_b32 v135, v117 offset:448
	s_waitcnt lgkmcnt(0)
	v_add_f32_e32 v128, v128, v129
	v_add_f32_e32 v130, v130, v131
	v_add_f32_e32 v132, v132, v133
	v_add_f32_e32 v134, v134, v135
	v_add_f32_e32 v128, v128, v130
	v_add_f32_e32 v132, v132, v134
	v_add_f32_e32 v128, v128, v132
	v_fmamk_f32 v128, v128, 0x3a000000, v79
	v_cmp_gt_f32_e32 vcc, s33, v128
	v_mul_f32_e32 v118, 0x4f800000, v128
	s_nop 1
	v_cndmask_b32_e32 v128, v128, v118, vcc
	v_sqrt_f32_e32 v118, v128
	s_nop 1
	v_add_u32_e32 v119, -1, v118
	v_fma_f32 v120, -v119, v118, v128
	v_cmp_ge_f32_e64 s[20:21], 0, v120
	v_add_u32_e32 v120, 1, v118
	s_nop 1
	v_cndmask_b32_e64 v119, v118, v119, s[20:21]
	v_fma_f32 v118, -v120, v118, v128
	v_cmp_lt_f32_e64 s[20:21], 0, v118
	s_nop 1
	v_cndmask_b32_e64 v118, v119, v120, s[20:21]
	v_mul_f32_e32 v119, 0x37800000, v118
	v_cndmask_b32_e32 v118, v118, v119, vcc
	v_cmp_class_f32_e32 vcc, v128, v80
	s_nop 1
	v_cndmask_b32_e32 v128, v118, v128, vcc
	v_div_scale_f32 v118, s[22:23], v128, v128, 1.0
	v_rcp_f32_e32 v119, v118
	s_nop 0
	v_fma_f32 v120, -v118, v119, 1.0
	v_fmac_f32_e32 v119, v120, v119
	v_div_scale_f32 v120, vcc, 1.0, v128, 1.0
	v_mul_f32_e32 v121, v120, v119
	v_fma_f32 v122, -v118, v121, v120
	v_fmac_f32_e32 v121, v122, v119
	v_fma_f32 v118, -v118, v121, v120
	v_div_fmas_f32 v118, v118, v119, v121
	v_div_fixup_f32 v118, v118, v128, 1.0
	v_readlane_b32 s12, v118, 0
	v_readlane_b32 s13, v118, 1
	v_readlane_b32 s14, v118, 2
	v_readlane_b32 s15, v118, 3
	v_readlane_b32 s16, v118, 4
	v_readlane_b32 s17, v118, 5
	v_readlane_b32 s18, v118, 6
	v_readlane_b32 s19, v118, 7
	s_nop 1
	v_mul_f32_e32 v4, s12, v4
	v_mul_f32_e32 v5, s12, v5
	v_mul_f32_e32 v6, s12, v6
	v_mul_f32_e32 v7, s12, v7
	v_pk_mul_f32 v[4:5], v[0:1], v[4:5]
	v_pk_mul_f32 v[6:7], v[2:3], v[6:7]
	v_lshl_add_u64 v[126:127], v[70:71], 0, s[24:25]
	global_store_dwordx4 v[126:127], v[4:7], off
	s_add_u32 s24, s24, 0x2000
	s_addc_u32 s25, s25, 0
	v_mul_f32_e32 v8, s13, v8
	v_mul_f32_e32 v9, s13, v9
	v_mul_f32_e32 v10, s13, v10
	v_mul_f32_e32 v11, s13, v11
	v_pk_mul_f32 v[8:9], v[0:1], v[8:9]
	v_pk_mul_f32 v[10:11], v[2:3], v[10:11]
	v_lshl_add_u64 v[126:127], v[70:71], 0, s[24:25]
	global_store_dwordx4 v[126:127], v[8:11], off
	s_add_u32 s24, s24, 0x2000
	s_addc_u32 s25, s25, 0
	v_mul_f32_e32 v12, s14, v12
	v_mul_f32_e32 v13, s14, v13
	v_mul_f32_e32 v14, s14, v14
	v_mul_f32_e32 v15, s14, v15
	v_pk_mul_f32 v[12:13], v[0:1], v[12:13]
	v_pk_mul_f32 v[14:15], v[2:3], v[14:15]
	v_lshl_add_u64 v[126:127], v[70:71], 0, s[24:25]
	global_store_dwordx4 v[126:127], v[12:15], off
	s_add_u32 s24, s24, 0x2000
	s_addc_u32 s25, s25, 0
	v_mul_f32_e32 v16, s15, v16
	v_mul_f32_e32 v17, s15, v17
	v_mul_f32_e32 v18, s15, v18
	v_mul_f32_e32 v19, s15, v19
	v_pk_mul_f32 v[16:17], v[0:1], v[16:17]
	v_pk_mul_f32 v[18:19], v[2:3], v[18:19]
	v_lshl_add_u64 v[126:127], v[70:71], 0, s[24:25]
	global_store_dwordx4 v[126:127], v[16:19], off
	s_add_u32 s24, s24, 0x2000
	s_addc_u32 s25, s25, 0
	v_mul_f32_e32 v20, s16, v20
	v_mul_f32_e32 v21, s16, v21
	v_mul_f32_e32 v22, s16, v22
	v_mul_f32_e32 v23, s16, v23
	v_pk_mul_f32 v[20:21], v[0:1], v[20:21]
	v_pk_mul_f32 v[22:23], v[2:3], v[22:23]
	v_lshl_add_u64 v[126:127], v[70:71], 0, s[24:25]
	global_store_dwordx4 v[126:127], v[20:23], off
	s_add_u32 s24, s24, 0x2000
	s_addc_u32 s25, s25, 0
	v_mul_f32_e32 v24, s17, v24
	v_mul_f32_e32 v25, s17, v25
	v_mul_f32_e32 v26, s17, v26
	v_mul_f32_e32 v27, s17, v27
	v_pk_mul_f32 v[24:25], v[0:1], v[24:25]
	v_pk_mul_f32 v[26:27], v[2:3], v[26:27]
	v_lshl_add_u64 v[126:127], v[70:71], 0, s[24:25]
	global_store_dwordx4 v[126:127], v[24:27], off
	s_add_u32 s24, s24, 0x2000
	s_addc_u32 s25, s25, 0
	v_mul_f32_e32 v28, s18, v28
	v_mul_f32_e32 v29, s18, v29
	v_mul_f32_e32 v30, s18, v30
	v_mul_f32_e32 v31, s18, v31
	v_pk_mul_f32 v[28:29], v[0:1], v[28:29]
	v_pk_mul_f32 v[30:31], v[2:3], v[30:31]
	v_lshl_add_u64 v[126:127], v[70:71], 0, s[24:25]
	global_store_dwordx4 v[126:127], v[28:31], off
	s_add_u32 s24, s24, 0x2000
	s_addc_u32 s25, s25, 0
	v_mul_f32_e32 v32, s19, v32
	v_mul_f32_e32 v33, s19, v33
	v_mul_f32_e32 v34, s19, v34
	v_mul_f32_e32 v35, s19, v35
	v_pk_mul_f32 v[32:33], v[0:1], v[32:33]
	v_pk_mul_f32 v[34:35], v[2:3], v[34:35]
	v_lshl_add_u64 v[126:127], v[70:71], 0, s[24:25]
	global_store_dwordx4 v[126:127], v[32:35], off
	s_add_u32 s24, s24, 0x2000
	s_addc_u32 s25, s25, 0
	v_readlane_b32 s12, v118, 8
	v_readlane_b32 s13, v118, 9
	v_readlane_b32 s14, v118, 10
	v_readlane_b32 s15, v118, 11
	v_readlane_b32 s16, v118, 12
	v_readlane_b32 s17, v118, 13
	v_readlane_b32 s18, v118, 14
	v_readlane_b32 s19, v118, 15
	s_nop 1
	v_mul_f32_e32 v36, s12, v36
	v_mul_f32_e32 v37, s12, v37
	v_mul_f32_e32 v38, s12, v38
	v_mul_f32_e32 v39, s12, v39
	v_pk_mul_f32 v[36:37], v[0:1], v[36:37]
	v_pk_mul_f32 v[38:39], v[2:3], v[38:39]
	v_lshl_add_u64 v[126:127], v[70:71], 0, s[24:25]
	global_store_dwordx4 v[126:127], v[36:39], off
	s_add_u32 s24, s24, 0x2000
	s_addc_u32 s25, s25, 0
	v_mul_f32_e32 v40, s13, v40
	v_mul_f32_e32 v41, s13, v41
	v_mul_f32_e32 v42, s13, v42
	v_mul_f32_e32 v43, s13, v43
	v_pk_mul_f32 v[40:41], v[0:1], v[40:41]
	v_pk_mul_f32 v[42:43], v[2:3], v[42:43]
	v_lshl_add_u64 v[126:127], v[70:71], 0, s[24:25]
	global_store_dwordx4 v[126:127], v[40:43], off
	s_add_u32 s24, s24, 0x2000
	s_addc_u32 s25, s25, 0
	v_mul_f32_e32 v44, s14, v44
	v_mul_f32_e32 v45, s14, v45
	v_mul_f32_e32 v46, s14, v46
	v_mul_f32_e32 v47, s14, v47
	v_pk_mul_f32 v[44:45], v[0:1], v[44:45]
	v_pk_mul_f32 v[46:47], v[2:3], v[46:47]
	v_lshl_add_u64 v[126:127], v[70:71], 0, s[24:25]
	global_store_dwordx4 v[126:127], v[44:47], off
	s_add_u32 s24, s24, 0x2000
	s_addc_u32 s25, s25, 0
	v_mul_f32_e32 v48, s15, v48
	v_mul_f32_e32 v49, s15, v49
	v_mul_f32_e32 v50, s15, v50
	v_mul_f32_e32 v51, s15, v51
	v_pk_mul_f32 v[48:49], v[0:1], v[48:49]
	v_pk_mul_f32 v[50:51], v[2:3], v[50:51]
	v_lshl_add_u64 v[126:127], v[70:71], 0, s[24:25]
	global_store_dwordx4 v[126:127], v[48:51], off
	s_add_u32 s24, s24, 0x2000
	s_addc_u32 s25, s25, 0
	v_mul_f32_e32 v52, s16, v52
	v_mul_f32_e32 v53, s16, v53
	v_mul_f32_e32 v54, s16, v54
	v_mul_f32_e32 v55, s16, v55
	v_pk_mul_f32 v[52:53], v[0:1], v[52:53]
	v_pk_mul_f32 v[54:55], v[2:3], v[54:55]
	v_lshl_add_u64 v[126:127], v[70:71], 0, s[24:25]
	global_store_dwordx4 v[126:127], v[52:55], off
	s_add_u32 s24, s24, 0x2000
	s_addc_u32 s25, s25, 0
	v_mul_f32_e32 v56, s17, v56
	v_mul_f32_e32 v57, s17, v57
	v_mul_f32_e32 v58, s17, v58
	v_mul_f32_e32 v59, s17, v59
	v_pk_mul_f32 v[56:57], v[0:1], v[56:57]
	v_pk_mul_f32 v[58:59], v[2:3], v[58:59]
	v_lshl_add_u64 v[126:127], v[70:71], 0, s[24:25]
	global_store_dwordx4 v[126:127], v[56:59], off
	s_add_u32 s24, s24, 0x2000
	s_addc_u32 s25, s25, 0
	v_mul_f32_e32 v60, s18, v60
	v_mul_f32_e32 v61, s18, v61
	v_mul_f32_e32 v62, s18, v62
	v_mul_f32_e32 v63, s18, v63
	v_pk_mul_f32 v[60:61], v[0:1], v[60:61]
	v_pk_mul_f32 v[62:63], v[2:3], v[62:63]
	v_lshl_add_u64 v[126:127], v[70:71], 0, s[24:25]
	global_store_dwordx4 v[126:127], v[60:63], off
	s_add_u32 s24, s24, 0x2000
	s_addc_u32 s25, s25, 0
	v_mul_f32_e32 v64, s19, v64
	v_mul_f32_e32 v65, s19, v65
	v_mul_f32_e32 v66, s19, v66
	v_mul_f32_e32 v67, s19, v67
	v_pk_mul_f32 v[64:65], v[0:1], v[64:65]
	v_pk_mul_f32 v[66:67], v[2:3], v[66:67]
	v_lshl_add_u64 v[126:127], v[70:71], 0, s[24:25]
	global_store_dwordx4 v[126:127], v[64:67], off
	s_add_u32 s24, s24, 0x2000
	s_addc_u32 s25, s25, 0
	s_waitcnt lgkmcnt(0)
	s_barrier
	s_add_i32 s2, s2, s34
	s_add_i32 s4, s4, s88
	s_cmpk_lt_i32 s2, 0x400
	s_cbranch_scc1 .Lnm_fin_loop
	s_branch .LBB0_1382
